# final norm row loop: counted-vmcnt double buffer - next row's 4 loads issued before this row's reduction (vmcnt(4) at the back-edge), on top of the permlane/DPP reductions
# speedup vs baseline: 1.0025x; 1.0025x over previous
; DI unsigned pack2(float a, float b) { f2_t v = {a, b}; return __builtin_bit_cast(unsigned, __builtin_convertvector(v, bf2_t)); }
; DI int otid() { int t = threadIdx.x; asm volatile("" : "+v"(t)); return t; }
; template <int MODE>
; DI void phase_norm(const float* xin, const float* g, const float* modl, int sh_off, int sc_off, u16* hout, float* fout) {
;   const int tid = otid(); const int lane = tid & 63, w = tid >> 6;
;   for (int row = blockIdx.x * NWAVE + w; row < NTOK; row += gridDim.x * NWAVE) {
;     const int b = row >> 14;
;     const float4* xr = (const float4*)(xin + (size_t)row * 1024);
;     float4 v[4];
; #pragma unroll
;     for (int i = 0; i < 4; ++i) v[i] = xr[lane + i * 64];
;     float ss = 0.f;
; #pragma unroll
;     for (int i = 0; i < 4; ++i) ss += v[i].x * v[i].x + v[i].y * v[i].y + v[i].z * v[i].z + v[i].w * v[i].w;
;     ss = wave_sum(ss);
;     const float inv = rsqrtf(ss * (1.f / 1024.f) + 1e-6f);
; #pragma unroll
;     for (int i = 0; i < 4; ++i) {
;       const int col = (lane + i * 64) * 4;
;       const float4 g4 = *(const float4*)(g + col);
;       if (MODE == 0) {
;         const float4 sc4 = *(const float4*)(modl + b * 6144 + sc_off + col);
;         const float4 sh4 = *(const float4*)(modl + b * 6144 + sh_off + col);
;         float y0 = v[i].x * inv * g4.x * (1.f + sc4.x) + sh4.x;
;         float y1 = v[i].y * inv * g4.y * (1.f + sc4.y) + sh4.y;
;         float y2 = v[i].z * inv * g4.z * (1.f + sc4.z) + sh4.z;
;         float y3 = v[i].w * inv * g4.w * (1.f + sc4.w) + sh4.w;
;         *(uint2*)(hout + (size_t)row * 1024 + col) = make_uint2(pack2(y0, y1), pack2(y2, y3));
;       } else {
;         float4 y; y.x = v[i].x * inv * g4.x; y.y = v[i].y * inv * g4.y; y.z = v[i].z * inv * g4.z; y.w = v[i].w * inv * g4.w;
;         *(float4*)(fout + (size_t)row * 1024 + col) = y;
.LBB0_841:
	v_readlane_b32 s0, v254, 4
	v_ashrrev_i32_e32 v0, 6, v224
	s_nop 0
	v_add_u32_e32 v0, s0, v0
	s_mov_b32 s0, 0x8000
	v_cmp_gt_i32_e32 vcc, s0, v0
	s_and_saveexec_b64 s[0:1], vcc
	s_cbranch_execz .LBB0_844
	s_load_dwordx4 s[4:7], s[82:83], 0x78
	v_and_b32_e32 v6, 63, v224
	v_mov_b32_e32 v3, 0
	v_lshlrev_b32_e32 v8, 2, v6
	v_lshlrev_b32_e32 v2, 4, v6
	s_waitcnt lgkmcnt(0)
	v_lshl_add_u64 v[4:5], s[4:5], 0, v[2:3]
	s_mov_b64 s[0:1], 0
	v_lshlrev_b32_e32 v2, 4, v6
	v_lshlrev_b32_e32 v6, 2, v8
	v_mov_b32_e32 v7, v3
	v_mov_b32_e32 v8, 0x358637bd
	s_mov_b32 s2, 0x800000
	s_movk_i32 s4, 0x7fff
	global_load_dwordx4 v[48:51], v[4:5], off
	global_load_dwordx4 v[52:55], v[4:5], off offset:1024
	global_load_dwordx4 v[56:59], v[4:5], off offset:2048
	global_load_dwordx4 v[60:63], v[4:5], off offset:3072
	v_ashrrev_i32_e32 v1, 31, v0
	v_lshlrev_b64 v[10:11], 12, v[0:1]
	v_lshl_add_u64 v[32:33], s[6:7], 0, v[10:11]
	v_lshl_add_u64 v[32:33], v[32:33], 0, v[2:3]
	global_load_dwordx4 v[64:67], v[32:33], off
	global_load_dwordx4 v[68:71], v[32:33], off offset:1024
	global_load_dwordx4 v[72:75], v[32:33], off offset:2048
	global_load_dwordx4 v[76:79], v[32:33], off offset:3072
	s_waitcnt vmcnt(0)
	s_branch .Lfn_body
.LBB0_843:
	s_waitcnt vmcnt(4)
.Lfn_body:
	v_mov_b32_e32 v10, v64
	v_mov_b32_e32 v11, v65
	v_mov_b32_e32 v12, v66
	v_mov_b32_e32 v13, v67
	v_mov_b32_e32 v14, v68
	v_mov_b32_e32 v15, v69
	v_mov_b32_e32 v16, v70
	v_mov_b32_e32 v17, v71
	v_mov_b32_e32 v18, v72
	v_mov_b32_e32 v19, v73
	v_mov_b32_e32 v20, v74
	v_mov_b32_e32 v21, v75
	v_mov_b32_e32 v22, v76
	v_mov_b32_e32 v23, v77
	v_mov_b32_e32 v24, v78
	v_mov_b32_e32 v25, v79
	v_ashrrev_i32_e32 v1, 31, v0
	v_lshlrev_b64 v[26:27], 12, v[0:1]
	v_lshl_add_u64 v[30:31], s[6:7], 0, v[26:27]
	v_lshl_add_u64 v[30:31], v[30:31], 0, v[6:7]
	v_add_u32_e32 v0, s3, v0
	v_min_i32_e32 v28, s4, v0
	v_ashrrev_i32_e32 v29, 31, v28
	v_lshlrev_b64 v[26:27], 12, v[28:29]
	v_lshl_add_u64 v[32:33], s[6:7], 0, v[26:27]
	v_lshl_add_u64 v[32:33], v[32:33], 0, v[2:3]
	global_load_dwordx4 v[64:67], v[32:33], off
	global_load_dwordx4 v[68:71], v[32:33], off offset:1024
	global_load_dwordx4 v[72:75], v[32:33], off offset:2048
	global_load_dwordx4 v[76:79], v[32:33], off offset:3072
	v_mov_b32_e32 v34, v11
	v_mov_b32_e32 v35, v15
	v_mov_b32_e32 v32, v10
	v_mov_b32_e32 v33, v14
	v_mov_b32_e32 v42, v19
	v_mov_b32_e32 v43, v23
	v_pk_mul_f32 v[34:35], v[34:35], v[34:35]
	v_mov_b32_e32 v36, v12
	v_mov_b32_e32 v37, v16
	v_mov_b32_e32 v40, v18
	v_mov_b32_e32 v41, v22
	v_pk_mul_f32 v[42:43], v[42:43], v[42:43]
	v_pk_fma_f32 v[32:33], v[32:33], v[32:33], v[34:35]
	v_mov_b32_e32 v38, v13
	v_mov_b32_e32 v39, v17
	v_mov_b32_e32 v44, v20
	v_mov_b32_e32 v45, v24
	v_pk_fma_f32 v[34:35], v[40:41], v[40:41], v[42:43]
	v_pk_fma_f32 v[32:33], v[36:37], v[36:37], v[32:33]
	v_mov_b32_e32 v46, v21
	v_mov_b32_e32 v47, v25
	v_pk_fma_f32 v[34:35], v[44:45], v[44:45], v[34:35]
	v_pk_fma_f32 v[32:33], v[38:39], v[38:39], v[32:33]
	v_pk_fma_f32 v[34:35], v[46:47], v[46:47], v[34:35]
	v_add_f32_e32 v1, v32, v33
	v_add_f32_e32 v1, v1, v34
	v_add_f32_e32 v1, v1, v35
	v_mov_b32_e32 v9, v1
	s_nop 1
	v_permlane32_swap_b32_e32 v9, v1
	s_nop 0
	v_add_f32_e32 v1, v1, v9
	v_mov_b32_e32 v9, v1
	s_nop 1
	v_permlane16_swap_b32_e32 v9, v1
	s_nop 0
	v_add_f32_e32 v1, v1, v9
	s_nop 1
	v_add_f32_dpp v1, v1, v1 row_ror:8 row_mask:0xf bank_mask:0xf
	s_nop 1
	v_add_f32_dpp v1, v1, v1 row_ror:4 row_mask:0xf bank_mask:0xf
	s_nop 1
	v_add_f32_dpp v1, v1, v1 row_ror:2 row_mask:0xf bank_mask:0xf
	s_nop 1
	v_add_f32_dpp v1, v1, v1 row_ror:1 row_mask:0xf bank_mask:0xf
	v_fmamk_f32 v1, v1, 0x3a800000, v8
	v_mul_f32_e32 v9, 0x4b800000, v1
	v_cmp_gt_f32_e32 vcc, s2, v1
	s_nop 1
	v_cndmask_b32_e32 v1, v1, v9, vcc
	v_rsq_f32_e32 v1, v1
	s_nop 0
	v_mul_f32_e32 v9, 0x45800000, v1
	v_cndmask_b32_e32 v32, v1, v9, vcc
	v_pk_mul_f32 v[10:11], v[10:11], v[32:33] op_sel_hi:[1,0]
	v_pk_mul_f32 v[12:13], v[12:13], v[32:33] op_sel_hi:[1,0]
	v_pk_mul_f32 v[10:11], v[48:49], v[10:11]
	v_pk_mul_f32 v[12:13], v[50:51], v[12:13]
	global_store_dwordx4 v[30:31], v[10:13], off
	s_nop 1
	v_pk_mul_f32 v[14:15], v[14:15], v[32:33] op_sel_hi:[1,0]
	v_pk_mul_f32 v[16:17], v[16:17], v[32:33] op_sel_hi:[1,0]
	v_cmp_lt_i32_e32 vcc, s4, v0
	s_or_b64 s[0:1], vcc, s[0:1]
	v_pk_mul_f32 v[10:11], v[52:53], v[14:15]
	v_pk_mul_f32 v[12:13], v[54:55], v[16:17]
	global_store_dwordx4 v[30:31], v[10:13], off offset:1024
	s_nop 1
	v_pk_mul_f32 v[14:15], v[18:19], v[32:33] op_sel_hi:[1,0]
	v_pk_mul_f32 v[16:17], v[20:21], v[32:33] op_sel_hi:[1,0]
	v_pk_mul_f32 v[10:11], v[14:15], v[56:57]
	v_pk_mul_f32 v[12:13], v[16:17], v[58:59]
	global_store_dwordx4 v[30:31], v[10:13], off offset:2048
	s_nop 1
	v_pk_mul_f32 v[14:15], v[22:23], v[32:33] op_sel_hi:[1,0]
	v_pk_mul_f32 v[16:17], v[24:25], v[32:33] op_sel_hi:[1,0]
	v_pk_mul_f32 v[10:11], v[14:15], v[60:61]
	v_pk_mul_f32 v[12:13], v[16:17], v[62:63]
	global_store_dwordx4 v[30:31], v[10:13], off offset:3072
	s_nop 1
	s_andn2_b64 exec, exec, s[0:1]
	s_cbranch_execnz .LBB0_843
